# static s_setprio 1 for the older wave half (waves 0-3) across the P2 attention phase (A/B of the per-half raise)
# speedup vs baseline: 1.0139x; 1.0139x over previous
.LBB0_337:
	s_or_b64 exec, exec, s[4:5]
	s_add_u32 s30, s92, 0xa800000
	s_addc_u32 s31, s93, 0
	s_cmpk_lt_i32 s33, 0x100
	s_cselect_b64 s[4:5], -1, 0
	s_cmpk_gt_i32 s33, 0xff
	s_mov_b32 s58, s80
	v_readlane_b32 s59, v239, 2
	s_waitcnt lgkmcnt(0)
	s_barrier
	v_mbcnt_lo_u32_b32 v170, -1, 0
	v_mbcnt_hi_u32_b32 v170, -1, v170
	s_cbranch_scc1 .LBB0_377
	s_mul_i32 s0, s81, 0x1200
	s_add_i32 s74, s0, 0
	s_mov_b32 s11, 0
	s_add_i32 s72, s74, 0x12800
	s_lshl_b32 s73, s81, 1
	s_add_i32 s74, s74, 0x1b800
	s_movk_i32 s75, 0x3000
	v_mov_b32_e32 v145, 0
	s_movk_i32 s76, 0x90
	v_mov_b32_e32 v171, 0xff800000
	s_mov_b32 s77, 0x3e38aa3b
	s_movk_i32 s82, 0x1000
	s_mov_b32 s83, s33
	s_cmp_gt_u32 s81, 3
	s_cbranch_scc1 .Lattn_prio_done
	s_setprio 1
